# attention QK LDS reads software-pipelined (MLA, Diff x2, FoX) + relaxed in-loop vmcnt
# speedup vs baseline: 1.0018x; 1.0018x over previous
; #define LAS __attribute__((address_space(3)))
; template <int DK, int MODE> ...
;     ...
;             const LAS char* kbase = K_lds + buf * SHM_K + r32 * PITCH;
; #pragma unroll
;             for (int d0 = 0; d0 < ND; ++d0) {
;                 const LAS char* a = kbase + (((d0 * 32 + hi * 16) ^ ((r32 & 7) << 4)));
;                 const bf16x8 b0 = *(const LAS bf16x8*)a, b1 = *(const LAS bf16x8*)(a + 32 * PITCH);
;                 p0 = __builtin_amdgcn_mfma_f32_32x32x16_bf16(b0, qr[d0], p0, 0, 0, 0);
;                 p1 = __builtin_amdgcn_mfma_f32_32x32x16_bf16(b1, qr[d0], p1, 0, 0, 0);
;             }
;             if (MODE == 1) {
; #pragma unroll
;                 for (int g = 0; g < 4; ++g) { const f32x4 fa = *(const LAS f32x4*)(fk_l + buf * 64 + 8 * g + 4 * hi), fb = *(const LAS f32x4*)(fk_l + buf * 64 + 32 + 8 * g + 4 * hi);
; #pragma unroll
;                     for (int i = 0; i < 4; ++i) { p0[4 * g + i] = fmaf(p0[4 * g + i], C2, Fq - fa[i]); p1[4 * g + i] = fmaf(p1[4 * g + i], C2, Fq - fb[i]); } }
;             }
.LBB0_868:
	s_sub_i32 s1, s86, 64
	s_cmp_gt_i32 s1, s2
	s_cbranch_scc1 .LBB0_876
	v_lshl_add_u32 v179, s0, 8, v175
	s_lshl_b32 s83, s0, 14
	ds_read_b128 v[82:85], v179
	ds_read_b128 v[86:89], v179 offset:32
	ds_read_b128 v[90:93], v179 offset:64
	ds_read_b128 v[94:97], v179 offset:96
	v_add_u32_e32 v180, s83, v165
	v_add_u32_e32 v181, v180, v166
	v_add_u32_e32 v182, v180, v167
	v_add_u32_e32 v183, v180, v168
	v_add_u32_e32 v245, v180, v169
	v_add_u32_e32 v248, v180, v170
	v_add_u32_e32 v250, v180, v171
	v_add_u32_e32 v251, v180, v172
	v_add_u32_e32 v252, v180, v173
	ds_read_b128 v[200:203], v181 offset:32768
	ds_read_b128 v[204:207], v182 offset:32768
	ds_read_b128 v[208:211], v183 offset:32768
	ds_read_b128 v[212:215], v245 offset:32768
	ds_read_b128 v[216:219], v248 offset:32768
	ds_read_b128 v[220:223], v250 offset:32768
	ds_read_b128 v[224:227], v251 offset:32768
	ds_read_b128 v[228:231], v252 offset:32768
	s_waitcnt lgkmcnt(8)
	v_sub_f32_e32 v159, v67, v83
	v_sub_f32_e32 v158, v66, v82
	v_sub_f32_e32 v157, v69, v85
	v_sub_f32_e32 v156, v68, v84
	v_sub_f32_e32 v155, v71, v87
	v_sub_f32_e32 v154, v70, v86
	v_sub_f32_e32 v153, v73, v89
	v_sub_f32_e32 v152, v72, v88
	v_sub_f32_e32 v145, v75, v91
	v_sub_f32_e32 v144, v74, v90
	v_sub_f32_e32 v143, v77, v93
	v_sub_f32_e32 v142, v76, v92
	v_sub_f32_e32 v161, v79, v95
	v_sub_f32_e32 v160, v78, v94
	v_sub_f32_e32 v163, v81, v97
	v_sub_f32_e32 v162, v80, v96
	s_waitcnt lgkmcnt(7)
	v_mfma_f32_32x32x16_bf16 v[82:97], v[200:203], v[98:101], 0
	ds_read_b128 v[200:203], v181 offset:40960
	s_waitcnt lgkmcnt(7)
	v_mfma_f32_32x32x16_bf16 v[82:97], v[204:207], v[102:105], v[82:97]
	ds_read_b128 v[204:207], v182 offset:40960
	s_waitcnt lgkmcnt(7)
	v_mfma_f32_32x32x16_bf16 v[82:97], v[208:211], v[106:109], v[82:97]
	ds_read_b128 v[208:211], v183 offset:40960
	s_waitcnt lgkmcnt(7)
	v_mfma_f32_32x32x16_bf16 v[82:97], v[212:215], v[110:113], v[82:97]
	ds_read_b128 v[212:215], v245 offset:40960
	s_waitcnt lgkmcnt(7)
	v_mfma_f32_32x32x16_bf16 v[82:97], v[216:219], v[114:117], v[82:97]
	ds_read_b128 v[216:219], v248 offset:40960
	s_waitcnt lgkmcnt(7)
	v_mfma_f32_32x32x16_bf16 v[82:97], v[220:223], v[118:121], v[82:97]
	ds_read_b128 v[220:223], v250 offset:40960
	s_waitcnt lgkmcnt(7)
	v_mfma_f32_32x32x16_bf16 v[82:97], v[224:227], v[122:125], v[82:97]
	ds_read_b128 v[224:227], v251 offset:40960
	s_waitcnt lgkmcnt(7)
	v_mfma_f32_32x32x16_bf16 v[82:97], v[228:231], v[126:129], v[82:97]
	ds_read_b128 v[228:231], v252 offset:40960
	ds_read_b128 v[184:187], v179 offset:128
	ds_read_b128 v[188:191], v179 offset:160
	ds_read_b128 v[232:235], v179 offset:192
	ds_read_b128 v[236:239], v179 offset:224
	s_nop 7
	v_pk_fma_f32 v[156:157], v[84:85], s[92:93], v[156:157] op_sel_hi:[1,0,1]
	v_pk_fma_f32 v[158:159], v[82:83], s[92:93], v[158:159] op_sel_hi:[1,0,1]
	v_pk_fma_f32 v[138:139], v[96:97], s[92:93], v[162:163] op_sel_hi:[1,0,1]
	v_pk_fma_f32 v[140:141], v[94:95], s[92:93], v[160:161] op_sel_hi:[1,0,1]
	v_pk_fma_f32 v[142:143], v[92:93], s[92:93], v[142:143] op_sel_hi:[1,0,1]
	v_pk_fma_f32 v[144:145], v[90:91], s[92:93], v[144:145] op_sel_hi:[1,0,1]
	v_pk_fma_f32 v[152:153], v[88:89], s[92:93], v[152:153] op_sel_hi:[1,0,1]
	v_pk_fma_f32 v[154:155], v[86:87], s[92:93], v[154:155] op_sel_hi:[1,0,1]
	s_waitcnt lgkmcnt(11)
	v_mfma_f32_32x32x16_bf16 v[82:97], v[200:203], v[98:101], 0
	s_waitcnt lgkmcnt(10)
	v_mfma_f32_32x32x16_bf16 v[82:97], v[204:207], v[102:105], v[82:97]
	s_waitcnt lgkmcnt(9)
	v_mfma_f32_32x32x16_bf16 v[82:97], v[208:211], v[106:109], v[82:97]
	s_waitcnt lgkmcnt(8)
	v_mfma_f32_32x32x16_bf16 v[82:97], v[212:215], v[110:113], v[82:97]
	s_waitcnt lgkmcnt(7)
	v_mfma_f32_32x32x16_bf16 v[82:97], v[216:219], v[114:117], v[82:97]
	s_waitcnt lgkmcnt(6)
	v_mfma_f32_32x32x16_bf16 v[82:97], v[220:223], v[118:121], v[82:97]
	s_waitcnt lgkmcnt(5)
	v_mfma_f32_32x32x16_bf16 v[82:97], v[224:227], v[122:125], v[82:97]
	s_waitcnt lgkmcnt(4)
	v_mfma_f32_32x32x16_bf16 v[82:97], v[228:231], v[126:129], v[82:97]
	s_waitcnt lgkmcnt(0)
	v_sub_f32_e32 v184, v66, v184
	v_sub_f32_e32 v185, v67, v185
	v_sub_f32_e32 v186, v68, v186
	v_sub_f32_e32 v187, v69, v187
	v_sub_f32_e32 v188, v70, v188
	v_sub_f32_e32 v189, v71, v189
	v_sub_f32_e32 v190, v72, v190
	v_sub_f32_e32 v191, v73, v191
	v_sub_f32_e32 v232, v74, v232
	v_sub_f32_e32 v233, v75, v233
	v_sub_f32_e32 v234, v76, v234
	v_sub_f32_e32 v235, v77, v235
	v_sub_f32_e32 v236, v78, v236
	v_sub_f32_e32 v237, v79, v237
	v_sub_f32_e32 v238, v80, v238
	v_sub_f32_e32 v239, v81, v239
	v_pk_fma_f32 v[82:83], v[82:83], s[92:93], v[184:185] op_sel_hi:[1,0,1]
	v_pk_fma_f32 v[84:85], v[84:85], s[92:93], v[186:187] op_sel_hi:[1,0,1]
	v_pk_fma_f32 v[86:87], v[86:87], s[92:93], v[188:189] op_sel_hi:[1,0,1]
	v_pk_fma_f32 v[88:89], v[88:89], s[92:93], v[190:191] op_sel_hi:[1,0,1]
	v_pk_fma_f32 v[90:91], v[90:91], s[92:93], v[232:233] op_sel_hi:[1,0,1]
	v_pk_fma_f32 v[92:93], v[92:93], s[92:93], v[234:235] op_sel_hi:[1,0,1]
	v_pk_fma_f32 v[94:95], v[94:95], s[92:93], v[236:237] op_sel_hi:[1,0,1]
	v_pk_fma_f32 v[96:97], v[96:97], s[92:93], v[238:239] op_sel_hi:[1,0,1]
	s_add_i32 s0, s86, -1
	s_cmp_le_i32 s0, s6
	s_cbranch_scc1 .LBB0_871
; template <int DK, int MODE> ...
;     ...
;             if (MODE != 2 && kb + 63 > qlo) {
;                 const float NEG = -__builtin_inff(); const int dq = qlo + r32 - kb - 4 * hi;
; #pragma unroll
;                 for (int r = 0; r < 16; ++r) { const int c = (r & 3) + 8 * (r >> 2); if (c > dq) p0[r] = NEG; if (c + 32 > dq) p1[r] = NEG; }
;             }
	v_cmp_gt_i32_e64 s[72:73], 26, v176
	v_cmp_gt_i32_e64 s[74:75], 27, v176
	v_cmp_gt_i32_e64 s[70:71], 25, v176
	s_and_b64 s[72:73], s[74:75], s[72:73]
	v_cmp_gt_i32_e64 s[68:69], 24, v176
	s_and_b64 s[70:71], s[72:73], s[70:71]
	v_cmp_gt_i32_e64 s[66:67], 19, v176
	s_and_b64 s[68:69], s[70:71], s[68:69]
	v_cmp_gt_i32_e64 s[64:65], 18, v176
	s_and_b64 s[66:67], s[68:69], s[66:67]
	v_cmp_gt_i32_e64 s[62:63], 17, v176
	s_and_b64 s[64:65], s[66:67], s[64:65]
	v_cmp_gt_i32_e64 s[60:61], 16, v176
	s_and_b64 s[62:63], s[64:65], s[62:63]
	v_cmp_gt_i32_e64 s[58:59], 11, v176
	s_and_b64 s[60:61], s[62:63], s[60:61]
	v_cmp_gt_i32_e64 s[56:57], 10, v176
	s_and_b64 s[58:59], s[60:61], s[58:59]
	v_cmp_gt_i32_e64 s[54:55], 9, v176
	s_and_b64 s[56:57], s[58:59], s[56:57]
	v_cmp_gt_i32_e64 s[52:53], 8, v176
	s_and_b64 s[54:55], s[56:57], s[54:55]
	v_cmp_gt_i32_e64 s[50:51], 3, v176
	s_and_b64 s[52:53], s[54:55], s[52:53]
	v_cmp_gt_i32_e64 s[48:49], 2, v176
	s_and_b64 s[50:51], s[52:53], s[50:51]
	v_cmp_gt_i32_e64 s[46:47], 1, v176
	s_and_b64 s[48:49], s[50:51], s[48:49]
	v_cmp_gt_i32_e64 s[44:45], 0, v176
	s_and_b64 s[46:47], s[48:49], s[46:47]
	s_and_b64 s[44:45], s[46:47], s[44:45]
	v_cmp_gt_i32_e64 s[40:41], 58, v176
	v_cndmask_b32_e64 v158, v158, v249, s[44:45]
	v_cmp_gt_i32_e64 s[44:45], 59, v176
	v_cmp_gt_i32_e64 s[38:39], 57, v176
	s_and_b64 s[40:41], s[44:45], s[40:41]
	v_cmp_gt_i32_e64 s[36:37], 56, v176
	s_and_b64 s[38:39], s[40:41], s[38:39]
	v_cmp_gt_i32_e64 s[34:35], 51, v176
	s_and_b64 s[36:37], s[38:39], s[36:37]
	v_cmp_gt_i32_e64 s[30:31], 50, v176
	s_and_b64 s[34:35], s[36:37], s[34:35]
	v_cmp_gt_i32_e64 s[28:29], 49, v176
	s_and_b64 s[30:31], s[34:35], s[30:31]
	v_cmp_gt_i32_e64 s[26:27], 48, v176
	s_and_b64 s[28:29], s[30:31], s[28:29]
	v_cmp_gt_i32_e64 s[24:25], 43, v176
	s_and_b64 s[26:27], s[28:29], s[26:27]
	v_cmp_gt_i32_e64 s[22:23], 42, v176
	s_and_b64 s[24:25], s[26:27], s[24:25]
	v_cmp_gt_i32_e64 s[20:21], 41, v176
	s_and_b64 s[22:23], s[24:25], s[22:23]
	v_cmp_gt_i32_e64 s[18:19], 40, v176
	s_and_b64 s[20:21], s[22:23], s[20:21]
	v_cmp_gt_i32_e64 s[16:17], 35, v176
	s_and_b64 s[18:19], s[20:21], s[18:19]
	v_cmp_gt_i32_e64 s[14:15], 34, v176
	s_and_b64 s[16:17], s[18:19], s[16:17]
	v_cmp_gt_i32_e64 s[12:13], 33, v176
	s_and_b64 s[14:15], s[16:17], s[14:15]
	v_cmp_gt_i32_e32 vcc, 32, v176
	s_and_b64 s[12:13], s[14:15], s[12:13]
	s_and_b64 vcc, s[12:13], vcc
	v_cndmask_b32_e64 v139, v139, v249, s[74:75]
	v_cndmask_b32_e64 v138, v138, v249, s[72:73]
	v_cndmask_b32_e64 v141, v141, v249, s[70:71]
	v_cndmask_b32_e64 v140, v140, v249, s[68:69]
	s_mov_b64 s[68:69], 0x98000
	v_cndmask_b32_e64 v143, v143, v249, s[66:67]
	v_readlane_b32 s66, v255, 33
	v_cndmask_b32_e64 v142, v142, v249, s[64:65]
	v_cndmask_b32_e64 v145, v145, v249, s[62:63]
	v_cndmask_b32_e64 v144, v144, v249, s[60:61]
	v_cndmask_b32_e64 v153, v153, v249, s[58:59]
	v_cndmask_b32_e64 v152, v152, v249, s[56:57]
	v_cndmask_b32_e64 v155, v155, v249, s[54:55]
	v_cndmask_b32_e64 v154, v154, v249, s[52:53]
	v_cndmask_b32_e64 v157, v157, v249, s[50:51]
	v_cndmask_b32_e64 v156, v156, v249, s[48:49]
	v_cndmask_b32_e64 v159, v159, v249, s[46:47]
	v_cndmask_b32_e64 v97, v97, v249, s[44:45]
	v_cndmask_b32_e64 v96, v96, v249, s[40:41]
	v_cndmask_b32_e64 v95, v95, v249, s[38:39]
	v_cndmask_b32_e64 v94, v94, v249, s[36:37]
	v_cndmask_b32_e64 v93, v93, v249, s[34:35]
	v_cndmask_b32_e64 v92, v92, v249, s[30:31]
	v_cndmask_b32_e64 v91, v91, v249, s[28:29]
	v_cndmask_b32_e64 v90, v90, v249, s[26:27]
	v_cndmask_b32_e64 v89, v89, v249, s[24:25]
	v_cndmask_b32_e64 v88, v88, v249, s[22:23]
	v_cndmask_b32_e64 v87, v87, v249, s[20:21]
	v_cndmask_b32_e64 v86, v86, v249, s[18:19]
	v_cndmask_b32_e64 v85, v85, v249, s[16:17]
	v_cndmask_b32_e64 v84, v84, v249, s[14:15]
	v_cndmask_b32_e64 v83, v83, v249, s[12:13]
	v_cndmask_b32_e32 v82, v82, v249, vcc

; #define LAS __attribute__((address_space(3)))
; template <int DK, int MODE> ...
;     ...
;             const LAS char* kbase = K_lds + buf * SHM_K + r32 * PITCH;
; #pragma unroll
;             for (int d0 = 0; d0 < ND; ++d0) {
;                 const LAS char* a = kbase + (((d0 * 32 + hi * 16) ^ ((r32 & 7) << 4)));
;                 const bf16x8 b0 = *(const LAS bf16x8*)a, b1 = *(const LAS bf16x8*)(a + 32 * PITCH);
;                 p0 = __builtin_amdgcn_mfma_f32_32x32x16_bf16(b0, qr[d0], p0, 0, 0, 0);
;                 p1 = __builtin_amdgcn_mfma_f32_32x32x16_bf16(b1, qr[d0], p1, 0, 0, 0);
;             }
;             if (MODE == 1) {
; #pragma unroll
;                 for (int g = 0; g < 4; ++g) { const f32x4 fa = *(const LAS f32x4*)(fk_l + buf * 64 + 8 * g + 4 * hi), fb = *(const LAS f32x4*)(fk_l + buf * 64 + 32 + 8 * g + 4 * hi);
; #pragma unroll
;                     for (int i = 0; i < 4; ++i) { p0[4 * g + i] = fmaf(p0[4 * g + i], C2, Fq - fa[i]); p1[4 * g + i] = fmaf(p1[4 * g + i], C2, Fq - fb[i]); } }
;             }
;             if (MODE != 2 && kb + 63 > qlo) {
;                 const float NEG = -__builtin_inff(); const int dq = qlo + r32 - kb - 4 * hi;
; #pragma unroll
;                 for (int r = 0; r < 16; ++r) { const int c = (r & 3) + 8 * (r >> 2); if (c > dq) p0[r] = NEG; if (c + 32 > dq) p1[r] = NEG; }
;             }
.LBB0_1014:
	s_sub_i32 s12, s43, 63
	s_cmp_gt_i32 s12, s86
	s_cbranch_scc1 .LBB0_1022
	v_lshl_add_u32 v127, s2, 13, v119
	v_add_u32_e32 v129, v127, v120
	v_add_u32_e32 v130, v127, v121
	v_add_u32_e32 v131, v127, v122
	v_add_u32_e32 v132, v127, v123
	ds_read_b128 v[200:203], v129 offset:32768
	ds_read_b128 v[204:207], v129 offset:36864
	ds_read_b128 v[208:211], v130 offset:32768
	ds_read_b128 v[212:215], v130 offset:36864
	ds_read_b128 v[216:219], v131 offset:32768
	ds_read_b128 v[220:223], v131 offset:36864
	ds_read_b128 v[224:227], v132 offset:32768
	ds_read_b128 v[228:231], v132 offset:36864
	s_waitcnt lgkmcnt(7)
	v_mfma_f32_32x32x16_bf16 v[66:81], v[200:203], v[98:101], 0
	s_waitcnt lgkmcnt(6)
	v_mfma_f32_32x32x16_bf16 v[82:97], v[204:207], v[98:101], 0
	s_waitcnt lgkmcnt(5)
	v_mfma_f32_32x32x16_bf16 v[66:81], v[208:211], v[102:105], v[66:81]
	s_waitcnt lgkmcnt(4)
	v_mfma_f32_32x32x16_bf16 v[82:97], v[212:215], v[102:105], v[82:97]
	s_waitcnt lgkmcnt(3)
	v_mfma_f32_32x32x16_bf16 v[66:81], v[216:219], v[106:109], v[66:81]
	s_waitcnt lgkmcnt(2)
	v_mfma_f32_32x32x16_bf16 v[82:97], v[220:223], v[106:109], v[82:97]
	s_waitcnt lgkmcnt(1)
	v_mfma_f32_32x32x16_bf16 v[66:81], v[224:227], v[110:113], v[66:81]
	s_waitcnt lgkmcnt(0)
	v_mfma_f32_32x32x16_bf16 v[82:97], v[228:231], v[110:113], v[82:97]
	s_cmp_le_i32 s43, s6
	s_cbranch_scc1 .LBB0_1017
	v_cmp_gt_i32_e64 s[72:73], 26, v125
	v_cmp_gt_i32_e64 s[74:75], 27, v125
	v_cmp_gt_i32_e64 s[70:71], 25, v125
	s_and_b64 s[72:73], s[74:75], s[72:73]
	v_cmp_gt_i32_e64 s[68:69], 24, v125
	s_and_b64 s[70:71], s[72:73], s[70:71]
	v_cmp_gt_i32_e64 s[66:67], 19, v125
	s_and_b64 s[68:69], s[70:71], s[68:69]
	v_cmp_gt_i32_e64 s[64:65], 18, v125
	s_and_b64 s[66:67], s[68:69], s[66:67]
	v_cmp_gt_i32_e64 s[62:63], 17, v125
	s_and_b64 s[64:65], s[66:67], s[64:65]
	v_cmp_gt_i32_e64 s[60:61], 16, v125
	s_and_b64 s[62:63], s[64:65], s[62:63]
	v_cmp_gt_i32_e64 s[58:59], 11, v125
	s_and_b64 s[60:61], s[62:63], s[60:61]
	v_cmp_gt_i32_e64 s[56:57], 10, v125
	s_and_b64 s[58:59], s[60:61], s[58:59]
	v_cmp_gt_i32_e64 s[54:55], 9, v125
	s_and_b64 s[56:57], s[58:59], s[56:57]
	v_cmp_gt_i32_e64 s[52:53], 8, v125
	s_and_b64 s[54:55], s[56:57], s[54:55]
	v_cmp_gt_i32_e64 s[50:51], 3, v125
	s_and_b64 s[52:53], s[54:55], s[52:53]
	v_cmp_gt_i32_e64 s[48:49], 2, v125
	s_and_b64 s[50:51], s[52:53], s[50:51]
	v_cmp_gt_i32_e64 s[46:47], 1, v125
	s_and_b64 s[48:49], s[50:51], s[48:49]
	v_cmp_gt_i32_e64 s[44:45], 0, v125
	s_and_b64 s[46:47], s[48:49], s[46:47]
	s_and_b64 s[44:45], s[46:47], s[44:45]
	v_cmp_gt_i32_e64 s[40:41], 58, v125
	v_cndmask_b32_e64 v66, v66, v249, s[44:45]
	v_cmp_gt_i32_e64 s[44:45], 59, v125
	v_cmp_gt_i32_e64 s[38:39], 57, v125
	s_and_b64 s[40:41], s[44:45], s[40:41]
	v_cmp_gt_i32_e64 s[36:37], 56, v125
	s_and_b64 s[38:39], s[40:41], s[38:39]
	v_cmp_gt_i32_e64 s[34:35], 51, v125
	s_and_b64 s[36:37], s[38:39], s[36:37]
	v_cmp_gt_i32_e64 s[30:31], 50, v125
	s_and_b64 s[34:35], s[36:37], s[34:35]
	v_cmp_gt_i32_e64 s[28:29], 49, v125
	s_and_b64 s[30:31], s[34:35], s[30:31]
	v_cmp_gt_i32_e64 s[26:27], 48, v125
	s_and_b64 s[28:29], s[30:31], s[28:29]
	v_cmp_gt_i32_e64 s[24:25], 43, v125
	s_and_b64 s[26:27], s[28:29], s[26:27]
	v_cmp_gt_i32_e64 s[22:23], 42, v125
	s_and_b64 s[24:25], s[26:27], s[24:25]
	v_cmp_gt_i32_e64 s[20:21], 41, v125
	s_and_b64 s[22:23], s[24:25], s[22:23]
	v_cmp_gt_i32_e64 s[18:19], 40, v125
	s_and_b64 s[20:21], s[22:23], s[20:21]
	v_cmp_gt_i32_e64 s[16:17], 35, v125
	s_and_b64 s[18:19], s[20:21], s[18:19]
	v_cmp_gt_i32_e64 s[14:15], 34, v125
	s_and_b64 s[16:17], s[18:19], s[16:17]
	v_cmp_gt_i32_e64 s[12:13], 33, v125
	s_and_b64 s[14:15], s[16:17], s[14:15]
	v_cmp_gt_i32_e32 vcc, 32, v125
	s_and_b64 s[12:13], s[14:15], s[12:13]
	s_and_b64 vcc, s[12:13], vcc
	v_cndmask_b32_e64 v81, v81, v249, s[74:75]
	v_cndmask_b32_e64 v80, v80, v249, s[72:73]
	v_cndmask_b32_e64 v79, v79, v249, s[70:71]
	v_cndmask_b32_e64 v78, v78, v249, s[68:69]
	s_mov_b64 s[68:69], 0x98000
	v_cndmask_b32_e64 v77, v77, v249, s[66:67]
	v_readlane_b32 s66, v255, 33
	v_cndmask_b32_e64 v76, v76, v249, s[64:65]
	v_cndmask_b32_e64 v75, v75, v249, s[62:63]
	v_cndmask_b32_e64 v74, v74, v249, s[60:61]
	v_cndmask_b32_e64 v73, v73, v249, s[58:59]
	v_cndmask_b32_e64 v72, v72, v249, s[56:57]
	v_cndmask_b32_e64 v71, v71, v249, s[54:55]
	v_cndmask_b32_e64 v70, v70, v249, s[52:53]
	v_cndmask_b32_e64 v69, v69, v249, s[50:51]
	v_cndmask_b32_e64 v68, v68, v249, s[48:49]
	v_cndmask_b32_e64 v67, v67, v249, s[46:47]
	v_cndmask_b32_e64 v97, v97, v249, s[44:45]
	v_cndmask_b32_e64 v96, v96, v249, s[40:41]
	v_cndmask_b32_e64 v95, v95, v249, s[38:39]
	v_cndmask_b32_e64 v94, v94, v249, s[36:37]
	v_cndmask_b32_e64 v93, v93, v249, s[34:35]
	v_cndmask_b32_e64 v92, v92, v249, s[30:31]
	v_cndmask_b32_e64 v91, v91, v249, s[28:29]
	v_cndmask_b32_e64 v90, v90, v249, s[26:27]
	v_cndmask_b32_e64 v89, v89, v249, s[24:25]
	v_cndmask_b32_e64 v88, v88, v249, s[22:23]
	v_cndmask_b32_e64 v87, v87, v249, s[20:21]
	v_cndmask_b32_e64 v86, v86, v249, s[18:19]
	v_cndmask_b32_e64 v85, v85, v249, s[16:17]
	v_cndmask_b32_e64 v84, v84, v249, s[14:15]
	v_cndmask_b32_e64 v83, v83, v249, s[12:13]
	v_cndmask_b32_e32 v82, v82, v249, vcc

; #define LAS __attribute__((address_space(3)))
; template <int DK, int MODE> ...
;     ...
;             const LAS char* kbase = K_lds + buf * SHM_K + r32 * PITCH;
; #pragma unroll
;             for (int d0 = 0; d0 < ND; ++d0) {
;                 const LAS char* a = kbase + (((d0 * 32 + hi * 16) ^ ((r32 & 7) << 4)));
;                 const bf16x8 b0 = *(const LAS bf16x8*)a, b1 = *(const LAS bf16x8*)(a + 32 * PITCH);
;                 p0 = __builtin_amdgcn_mfma_f32_32x32x16_bf16(b0, qr[d0], p0, 0, 0, 0);
;                 p1 = __builtin_amdgcn_mfma_f32_32x32x16_bf16(b1, qr[d0], p1, 0, 0, 0);
;             }
;             if (MODE == 1) {
; #pragma unroll
;                 for (int g = 0; g < 4; ++g) { const f32x4 fa = *(const LAS f32x4*)(fk_l + buf * 64 + 8 * g + 4 * hi), fb = *(const LAS f32x4*)(fk_l + buf * 64 + 32 + 8 * g + 4 * hi);
; #pragma unroll
;                     for (int i = 0; i < 4; ++i) { p0[4 * g + i] = fmaf(p0[4 * g + i], C2, Fq - fa[i]); p1[4 * g + i] = fmaf(p1[4 * g + i], C2, Fq - fb[i]); } }
;             }
;             if (MODE != 2 && kb + 63 > qlo) {
;                 const float NEG = -__builtin_inff(); const int dq = qlo + r32 - kb - 4 * hi;
; #pragma unroll
;                 for (int r = 0; r < 16; ++r) { const int c = (r & 3) + 8 * (r >> 2); if (c > dq) p0[r] = NEG; if (c + 32 > dq) p1[r] = NEG; }
;             }
.LBB0_1029:
	s_sub_i32 s0, s43, 63
	s_cmp_gt_i32 s0, s86
	s_cbranch_scc1 .LBB0_1037
	v_lshl_add_u32 v165, s2, 13, v157
	v_add_u32_e32 v167, v165, v158
	v_add_u32_e32 v168, v165, v159
	v_add_u32_e32 v169, v165, v160
	v_add_u32_e32 v170, v165, v161
	ds_read_b128 v[200:203], v167 offset:32768
	ds_read_b128 v[204:207], v167 offset:36864
	ds_read_b128 v[208:211], v168 offset:32768
	ds_read_b128 v[212:215], v168 offset:36864
	ds_read_b128 v[216:219], v169 offset:32768
	ds_read_b128 v[220:223], v169 offset:36864
	ds_read_b128 v[224:227], v170 offset:32768
	ds_read_b128 v[228:231], v170 offset:36864
	s_waitcnt lgkmcnt(7)
	v_mfma_f32_32x32x16_bf16 v[66:81], v[200:203], v[98:101], 0
	s_waitcnt lgkmcnt(6)
	v_mfma_f32_32x32x16_bf16 v[82:97], v[204:207], v[98:101], 0
	s_waitcnt lgkmcnt(5)
	v_mfma_f32_32x32x16_bf16 v[66:81], v[208:211], v[102:105], v[66:81]
	s_waitcnt lgkmcnt(4)
	v_mfma_f32_32x32x16_bf16 v[82:97], v[212:215], v[102:105], v[82:97]
	s_waitcnt lgkmcnt(3)
	v_mfma_f32_32x32x16_bf16 v[66:81], v[216:219], v[106:109], v[66:81]
	s_waitcnt lgkmcnt(2)
	v_mfma_f32_32x32x16_bf16 v[82:97], v[220:223], v[106:109], v[82:97]
	s_waitcnt lgkmcnt(1)
	v_mfma_f32_32x32x16_bf16 v[66:81], v[224:227], v[110:113], v[66:81]
	s_waitcnt lgkmcnt(0)
	v_mfma_f32_32x32x16_bf16 v[82:97], v[228:231], v[110:113], v[82:97]
	s_cmp_le_i32 s43, s6
	s_cbranch_scc1 .LBB0_1032
	v_cmp_gt_i32_e64 s[72:73], 26, v163
	v_cmp_gt_i32_e64 s[74:75], 27, v163
	v_cmp_gt_i32_e64 s[70:71], 25, v163
	s_and_b64 s[72:73], s[74:75], s[72:73]
	v_cmp_gt_i32_e64 s[68:69], 24, v163
	s_and_b64 s[70:71], s[72:73], s[70:71]
	v_cmp_gt_i32_e64 s[66:67], 19, v163
	s_and_b64 s[68:69], s[70:71], s[68:69]
	v_cmp_gt_i32_e64 s[64:65], 18, v163
	s_and_b64 s[66:67], s[68:69], s[66:67]
	v_cmp_gt_i32_e64 s[62:63], 17, v163
	s_and_b64 s[64:65], s[66:67], s[64:65]
	v_cmp_gt_i32_e64 s[60:61], 16, v163
	s_and_b64 s[62:63], s[64:65], s[62:63]
	v_cmp_gt_i32_e64 s[58:59], 11, v163
	s_and_b64 s[60:61], s[62:63], s[60:61]
	v_cmp_gt_i32_e64 s[56:57], 10, v163
	s_and_b64 s[58:59], s[60:61], s[58:59]
	v_cmp_gt_i32_e64 s[54:55], 9, v163
	s_and_b64 s[56:57], s[58:59], s[56:57]
	v_cmp_gt_i32_e64 s[52:53], 8, v163
	s_and_b64 s[54:55], s[56:57], s[54:55]
	v_cmp_gt_i32_e64 s[50:51], 3, v163
	s_and_b64 s[52:53], s[54:55], s[52:53]
	v_cmp_gt_i32_e64 s[48:49], 2, v163
	s_and_b64 s[50:51], s[52:53], s[50:51]
	v_cmp_gt_i32_e64 s[46:47], 1, v163
	s_and_b64 s[48:49], s[50:51], s[48:49]
	v_cmp_gt_i32_e64 s[44:45], 0, v163
	s_and_b64 s[46:47], s[48:49], s[46:47]
	s_and_b64 s[44:45], s[46:47], s[44:45]
	v_cmp_gt_i32_e64 s[40:41], 58, v163
	v_cndmask_b32_e64 v66, v66, v249, s[44:45]
	v_cmp_gt_i32_e64 s[44:45], 59, v163
	v_cmp_gt_i32_e64 s[38:39], 57, v163
	s_and_b64 s[40:41], s[44:45], s[40:41]
	v_cmp_gt_i32_e64 s[36:37], 56, v163
	s_and_b64 s[38:39], s[40:41], s[38:39]
	v_cmp_gt_i32_e64 s[34:35], 51, v163
	s_and_b64 s[36:37], s[38:39], s[36:37]
	v_cmp_gt_i32_e64 s[30:31], 50, v163
	s_and_b64 s[34:35], s[36:37], s[34:35]
	v_cmp_gt_i32_e64 s[28:29], 49, v163
	s_and_b64 s[30:31], s[34:35], s[30:31]
	v_cmp_gt_i32_e64 s[26:27], 48, v163
	s_and_b64 s[28:29], s[30:31], s[28:29]
	v_cmp_gt_i32_e64 s[24:25], 43, v163
	s_and_b64 s[26:27], s[28:29], s[26:27]
	v_cmp_gt_i32_e64 s[22:23], 42, v163
	s_and_b64 s[24:25], s[26:27], s[24:25]
	v_cmp_gt_i32_e64 s[20:21], 41, v163
	s_and_b64 s[22:23], s[24:25], s[22:23]
	v_cmp_gt_i32_e64 s[18:19], 40, v163
	s_and_b64 s[20:21], s[22:23], s[20:21]
	v_cmp_gt_i32_e64 s[16:17], 35, v163
	s_and_b64 s[18:19], s[20:21], s[18:19]
	v_cmp_gt_i32_e64 s[14:15], 34, v163
	s_and_b64 s[16:17], s[18:19], s[16:17]
	v_cmp_gt_i32_e64 s[12:13], 33, v163
	s_and_b64 s[14:15], s[16:17], s[14:15]
	v_cmp_gt_i32_e32 vcc, 32, v163
	s_and_b64 s[12:13], s[14:15], s[12:13]
	s_and_b64 vcc, s[12:13], vcc
	v_cndmask_b32_e64 v81, v81, v249, s[74:75]
	v_cndmask_b32_e64 v80, v80, v249, s[72:73]
	v_cndmask_b32_e64 v79, v79, v249, s[70:71]
	v_cndmask_b32_e64 v78, v78, v249, s[68:69]
	s_mov_b64 s[68:69], 0x98000
	v_cndmask_b32_e64 v77, v77, v249, s[66:67]
	v_readlane_b32 s66, v255, 33
	v_cndmask_b32_e64 v76, v76, v249, s[64:65]
	v_cndmask_b32_e64 v75, v75, v249, s[62:63]
	v_cndmask_b32_e64 v74, v74, v249, s[60:61]
	v_cndmask_b32_e64 v73, v73, v249, s[58:59]
	v_cndmask_b32_e64 v72, v72, v249, s[56:57]
	v_cndmask_b32_e64 v71, v71, v249, s[54:55]
	v_cndmask_b32_e64 v70, v70, v249, s[52:53]
	v_cndmask_b32_e64 v69, v69, v249, s[50:51]
	v_cndmask_b32_e64 v68, v68, v249, s[48:49]
	v_cndmask_b32_e64 v67, v67, v249, s[46:47]
	v_cndmask_b32_e64 v97, v97, v249, s[44:45]
	v_cndmask_b32_e64 v96, v96, v249, s[40:41]
	v_cndmask_b32_e64 v95, v95, v249, s[38:39]
	v_cndmask_b32_e64 v94, v94, v249, s[36:37]
	v_cndmask_b32_e64 v93, v93, v249, s[34:35]
	v_cndmask_b32_e64 v92, v92, v249, s[30:31]
	v_cndmask_b32_e64 v91, v91, v249, s[28:29]
	v_cndmask_b32_e64 v90, v90, v249, s[26:27]
	v_cndmask_b32_e64 v89, v89, v249, s[24:25]
	v_cndmask_b32_e64 v88, v88, v249, s[22:23]
	v_cndmask_b32_e64 v87, v87, v249, s[20:21]
	v_cndmask_b32_e64 v86, v86, v249, s[18:19]
	v_cndmask_b32_e64 v85, v85, v249, s[16:17]
	v_cndmask_b32_e64 v84, v84, v249, s[14:15]
	v_cndmask_b32_e64 v83, v83, v249, s[12:13]
	v_cndmask_b32_e32 v82, v82, v249, vcc

; #define LAS __attribute__((address_space(3)))
; template <int DK, int MODE> ...
;     ...
;             const LAS char* kbase = K_lds + buf * SHM_K + r32 * PITCH;
; #pragma unroll
;             for (int d0 = 0; d0 < ND; ++d0) {
;                 const LAS char* a = kbase + (((d0 * 32 + hi * 16) ^ ((r32 & 7) << 4)));
;                 const bf16x8 b0 = *(const LAS bf16x8*)a, b1 = *(const LAS bf16x8*)(a + 32 * PITCH);
;                 p0 = __builtin_amdgcn_mfma_f32_32x32x16_bf16(b0, qr[d0], p0, 0, 0, 0);
;                 p1 = __builtin_amdgcn_mfma_f32_32x32x16_bf16(b1, qr[d0], p1, 0, 0, 0);
;             }
.LBB0_1186:
	s_sub_i32 s0, s82, 63
	s_cmp_gt_i32 s0, s79
	s_cbranch_scc1 .LBB0_1194
	s_mul_i32 s0, s5, 0x6000
	v_add_u32_e32 v182, s0, v166
	v_add_u32_e32 v188, v182, v167
	v_add_u32_e32 v189, v182, v168
	v_add_u32_e32 v190, v182, v169
	v_add_u32_e32 v191, v182, v170
	v_add_u32_e32 v184, v182, v171
	ds_read_b128 v[200:203], v188 offset:32768
	ds_read_b128 v[204:207], v188 offset:45056
	ds_read_b128 v[208:211], v189 offset:32768
	ds_read_b128 v[212:215], v189 offset:45056
	ds_read_b128 v[216:219], v190 offset:32768
	ds_read_b128 v[220:223], v190 offset:45056
	ds_read_b128 v[224:227], v191 offset:32768
	ds_read_b128 v[228:231], v191 offset:45056
	ds_read_b128 v[232:235], v184 offset:32768
	ds_read_b128 v[236:239], v184 offset:45056
	s_waitcnt lgkmcnt(9)
	v_mfma_f32_32x32x16_bf16 v[66:81], v[200:203], v[98:101], 0
	v_add_u32_e32 v185, v182, v172
	ds_read_b128 v[200:203], v185 offset:32768
	s_waitcnt lgkmcnt(9)
	v_mfma_f32_32x32x16_bf16 v[82:97], v[204:207], v[98:101], 0
	ds_read_b128 v[204:207], v185 offset:45056
	s_waitcnt lgkmcnt(9)
	v_mfma_f32_32x32x16_bf16 v[66:81], v[208:211], v[102:105], v[66:81]
	v_add_u32_e32 v186, v182, v173
	ds_read_b128 v[208:211], v186 offset:32768
	s_waitcnt lgkmcnt(9)
	v_mfma_f32_32x32x16_bf16 v[82:97], v[212:215], v[102:105], v[82:97]
	ds_read_b128 v[212:215], v186 offset:45056
	s_waitcnt lgkmcnt(9)
	v_mfma_f32_32x32x16_bf16 v[66:81], v[216:219], v[106:109], v[66:81]
	v_add_u32_e32 v187, v182, v174
	ds_read_b128 v[216:219], v187 offset:32768
	s_waitcnt lgkmcnt(9)
	v_mfma_f32_32x32x16_bf16 v[82:97], v[220:223], v[106:109], v[82:97]
	ds_read_b128 v[220:223], v187 offset:45056
	s_waitcnt lgkmcnt(9)
	v_mfma_f32_32x32x16_bf16 v[66:81], v[224:227], v[110:113], v[66:81]
	v_add_u32_e32 v188, v182, v175
	ds_read_b128 v[224:227], v188 offset:32768
	s_waitcnt lgkmcnt(9)
	v_mfma_f32_32x32x16_bf16 v[82:97], v[228:231], v[110:113], v[82:97]
	ds_read_b128 v[228:231], v188 offset:45056
	s_waitcnt lgkmcnt(9)
	v_mfma_f32_32x32x16_bf16 v[66:81], v[232:235], v[114:117], v[66:81]
	v_add_u32_e32 v189, v182, v176
	ds_read_b128 v[232:235], v189 offset:32768
	s_waitcnt lgkmcnt(9)
	v_mfma_f32_32x32x16_bf16 v[82:97], v[236:239], v[114:117], v[82:97]
	ds_read_b128 v[236:239], v189 offset:45056
	s_waitcnt lgkmcnt(9)
	v_mfma_f32_32x32x16_bf16 v[66:81], v[200:203], v[118:121], v[66:81]
	v_add_u32_e32 v190, v182, v177
	ds_read_b128 v[200:203], v190 offset:32768
	s_waitcnt lgkmcnt(9)
	v_mfma_f32_32x32x16_bf16 v[82:97], v[204:207], v[118:121], v[82:97]
	ds_read_b128 v[204:207], v190 offset:45056
	s_waitcnt lgkmcnt(9)
	v_mfma_f32_32x32x16_bf16 v[66:81], v[208:211], v[122:125], v[66:81]
	v_add_u32_e32 v191, v182, v178
	ds_read_b128 v[208:211], v191 offset:32768
	s_waitcnt lgkmcnt(9)
	v_mfma_f32_32x32x16_bf16 v[82:97], v[212:215], v[122:125], v[82:97]
	ds_read_b128 v[212:215], v191 offset:45056
	s_waitcnt lgkmcnt(9)
	v_mfma_f32_32x32x16_bf16 v[66:81], v[216:219], v[126:129], v[66:81]
	s_waitcnt lgkmcnt(8)
	v_mfma_f32_32x32x16_bf16 v[82:97], v[220:223], v[126:129], v[82:97]
	s_waitcnt lgkmcnt(7)
	v_mfma_f32_32x32x16_bf16 v[66:81], v[224:227], v[130:133], v[66:81]
	s_waitcnt lgkmcnt(6)
	v_mfma_f32_32x32x16_bf16 v[82:97], v[228:231], v[130:133], v[82:97]
	s_waitcnt lgkmcnt(5)
	v_mfma_f32_32x32x16_bf16 v[66:81], v[232:235], v[134:137], v[66:81]
	s_waitcnt lgkmcnt(4)
	v_mfma_f32_32x32x16_bf16 v[82:97], v[236:239], v[134:137], v[82:97]
	s_waitcnt lgkmcnt(3)
	v_mfma_f32_32x32x16_bf16 v[66:81], v[200:203], v[138:141], v[66:81]
	s_waitcnt lgkmcnt(2)
	v_mfma_f32_32x32x16_bf16 v[82:97], v[204:207], v[138:141], v[82:97]
	s_waitcnt lgkmcnt(1)
	v_mfma_f32_32x32x16_bf16 v[66:81], v[208:211], v[142:145], v[66:81]
	s_waitcnt lgkmcnt(0)
	v_mfma_f32_32x32x16_bf16 v[82:97], v[212:215], v[142:145], v[82:97]
	s_cmp_le_i32 s82, s6
	s_cbranch_scc1 .LBB0_1189
; template <int DK, int MODE> ...
;     ...
;             if (MODE != 2 && kb + 63 > qlo) {
;                 const float NEG = -__builtin_inff(); const int dq = qlo + r32 - kb - 4 * hi;
; #pragma unroll
;                 for (int r = 0; r < 16; ++r) { const int c = (r & 3) + 8 * (r >> 2); if (c > dq) p0[r] = NEG; if (c + 32 > dq) p1[r] = NEG; }
;             }
	v_cmp_gt_i32_e64 s[72:73], 26, v180
	v_cmp_gt_i32_e64 s[74:75], 27, v180
	v_cmp_gt_i32_e64 s[70:71], 25, v180
	s_and_b64 s[72:73], s[74:75], s[72:73]
	v_cmp_gt_i32_e64 s[68:69], 24, v180
	s_and_b64 s[70:71], s[72:73], s[70:71]
	v_cmp_gt_i32_e64 s[66:67], 19, v180
	s_and_b64 s[68:69], s[70:71], s[68:69]
	v_cmp_gt_i32_e64 s[64:65], 18, v180
	s_and_b64 s[66:67], s[68:69], s[66:67]
	v_cmp_gt_i32_e64 s[62:63], 17, v180
	s_and_b64 s[64:65], s[66:67], s[64:65]
	v_cmp_gt_i32_e64 s[60:61], 16, v180
	s_and_b64 s[62:63], s[64:65], s[62:63]
	v_cmp_gt_i32_e64 s[58:59], 11, v180
	s_and_b64 s[60:61], s[62:63], s[60:61]
	v_cmp_gt_i32_e64 s[56:57], 10, v180
	s_and_b64 s[58:59], s[60:61], s[58:59]
	v_cmp_gt_i32_e64 s[54:55], 9, v180
	s_and_b64 s[56:57], s[58:59], s[56:57]
	v_cmp_gt_i32_e64 s[52:53], 8, v180
	s_and_b64 s[54:55], s[56:57], s[54:55]
	v_cmp_gt_i32_e64 s[50:51], 3, v180
	s_and_b64 s[52:53], s[54:55], s[52:53]
	v_cmp_gt_i32_e64 s[48:49], 2, v180
	s_and_b64 s[50:51], s[52:53], s[50:51]
	v_cmp_gt_i32_e64 s[46:47], 1, v180
	s_and_b64 s[48:49], s[50:51], s[48:49]
	v_cmp_gt_i32_e64 s[44:45], 0, v180
	s_and_b64 s[46:47], s[48:49], s[46:47]
	s_and_b64 s[44:45], s[46:47], s[44:45]
	v_cmp_gt_i32_e64 s[40:41], 58, v180
	v_cndmask_b32_e64 v66, v66, v249, s[44:45]
	v_cmp_gt_i32_e64 s[44:45], 59, v180
	v_cmp_gt_i32_e64 s[38:39], 57, v180
	s_and_b64 s[40:41], s[44:45], s[40:41]
	v_cmp_gt_i32_e64 s[36:37], 56, v180
	s_and_b64 s[38:39], s[40:41], s[38:39]
	v_cmp_gt_i32_e64 s[34:35], 51, v180
	s_and_b64 s[36:37], s[38:39], s[36:37]
	v_cmp_gt_i32_e64 s[30:31], 50, v180
	s_and_b64 s[34:35], s[36:37], s[34:35]
	v_cmp_gt_i32_e64 s[28:29], 49, v180
	s_and_b64 s[30:31], s[34:35], s[30:31]
	v_cmp_gt_i32_e64 s[26:27], 48, v180
	s_and_b64 s[28:29], s[30:31], s[28:29]
	v_cmp_gt_i32_e64 s[24:25], 43, v180
	s_and_b64 s[26:27], s[28:29], s[26:27]
	v_cmp_gt_i32_e64 s[22:23], 42, v180
	s_and_b64 s[24:25], s[26:27], s[24:25]
	v_cmp_gt_i32_e64 s[20:21], 41, v180
	s_and_b64 s[22:23], s[24:25], s[22:23]
	v_cmp_gt_i32_e64 s[18:19], 40, v180
	s_and_b64 s[20:21], s[22:23], s[20:21]
	v_cmp_gt_i32_e64 s[16:17], 35, v180
	s_and_b64 s[18:19], s[20:21], s[18:19]
	v_cmp_gt_i32_e64 s[14:15], 34, v180
	s_and_b64 s[16:17], s[18:19], s[16:17]
	v_cmp_gt_i32_e64 s[12:13], 33, v180
	s_and_b64 s[14:15], s[16:17], s[14:15]
	v_cmp_gt_i32_e32 vcc, 32, v180
	s_and_b64 s[12:13], s[14:15], s[12:13]
	s_and_b64 vcc, s[12:13], vcc
	v_cndmask_b32_e64 v81, v81, v249, s[74:75]
	v_cndmask_b32_e64 v80, v80, v249, s[72:73]
	v_cndmask_b32_e64 v79, v79, v249, s[70:71]
	v_cndmask_b32_e64 v78, v78, v249, s[68:69]
	s_mov_b64 s[68:69], 0x98000
	v_cndmask_b32_e64 v77, v77, v249, s[66:67]
	v_readlane_b32 s66, v255, 33
	v_cndmask_b32_e64 v76, v76, v249, s[64:65]
	v_cndmask_b32_e64 v75, v75, v249, s[62:63]
	v_cndmask_b32_e64 v74, v74, v249, s[60:61]
	v_cndmask_b32_e64 v73, v73, v249, s[58:59]
	v_cndmask_b32_e64 v72, v72, v249, s[56:57]
	v_cndmask_b32_e64 v71, v71, v249, s[54:55]
	v_cndmask_b32_e64 v70, v70, v249, s[52:53]
	v_cndmask_b32_e64 v69, v69, v249, s[50:51]
	v_cndmask_b32_e64 v68, v68, v249, s[48:49]
	v_cndmask_b32_e64 v67, v67, v249, s[46:47]
	v_cndmask_b32_e64 v97, v97, v249, s[44:45]
	v_cndmask_b32_e64 v96, v96, v249, s[40:41]
	v_cndmask_b32_e64 v95, v95, v249, s[38:39]
	v_cndmask_b32_e64 v94, v94, v249, s[36:37]
	v_cndmask_b32_e64 v93, v93, v249, s[34:35]
	v_cndmask_b32_e64 v92, v92, v249, s[30:31]
	v_cndmask_b32_e64 v91, v91, v249, s[28:29]
	v_cndmask_b32_e64 v90, v90, v249, s[26:27]
	v_cndmask_b32_e64 v89, v89, v249, s[24:25]
	v_cndmask_b32_e64 v88, v88, v249, s[22:23]
	v_cndmask_b32_e64 v87, v87, v249, s[20:21]
	v_cndmask_b32_e64 v86, v86, v249, s[18:19]
	v_cndmask_b32_e64 v85, v85, v249, s[16:17]
	v_cndmask_b32_e64 v84, v84, v249, s[14:15]
	v_cndmask_b32_e64 v83, v83, v249, s[12:13]
	v_cndmask_b32_e32 v82, v82, v249, vcc
